# prep phase: adaLN GEMV pipelined (12 staging loads batched, 3 weight-loop iterations in flight) and prep work rebalanced (GEMV / DFT-fold blocks take no conversion tiles; blocks 320..511 take six each
# speedup vs baseline: 1.2975x; 1.0132x over previous
; __device__ __forceinline__ float silu_f(float x) { return x / (1.f + __expf(-x)); }
; __device__ __forceinline__ void ada_item(const Params& p, int it, unsigned char* smem) {
;     ...
; #pragma unroll
;   for (int i = 0; i < 12; ++i) {
;     const int idx = t + 256 * i, r = idx >> 10, k = idx & 1023;
;     const float cv = r < 2 ? p.c[r * 1024 + k] : p.c_ctx[k];
;     sc[idx] = silu_f(cv);
;   }
;   __syncthreads();
.LBB0_8:
	v_mov_b32_e32 v6, v187
	global_load_dwordx2 v[10:11], v[2:3], off offset:8
	global_load_dwordx2 v[8:9], v[2:3], off offset:24
	v_lshlrev_b32_e32 v7, 2, v6
	v_lshlrev_b32_e32 v58, 2, v6
	v_mov_b32_e32 v59, 0
	s_mov_b64 s[30:31], 0
	s_waitcnt vmcnt(0)
	v_lshl_add_u64 v[60:61], v[10:11], 0, v[58:59]
	v_lshl_add_u64 v[62:63], v[8:9], 0, v[58:59]
	v_lshl_add_u64 v[64:65], v[60:61], 0, s[12:13]
	global_load_dword v66, v[60:61], off offset:0
	global_load_dword v67, v[60:61], off offset:1024
	global_load_dword v68, v[60:61], off offset:2048
	global_load_dword v69, v[60:61], off offset:3072
	global_load_dword v70, v[64:65], off offset:0
	global_load_dword v71, v[64:65], off offset:1024
	global_load_dword v72, v[64:65], off offset:2048
	global_load_dword v73, v[64:65], off offset:3072
	global_load_dword v74, v[62:63], off offset:0
	global_load_dword v75, v[62:63], off offset:1024
	global_load_dword v76, v[62:63], off offset:2048
	global_load_dword v77, v[62:63], off offset:3072
	s_waitcnt vmcnt(0)
	v_mul_f32_e32 v16, 0xbfb8aa3b, v66
	v_exp_f32_e32 v19, v16
	s_nop 0
	v_add_f32_e32 v4, 1.0, v19
	v_div_scale_f32 v17, s[28:29], v4, v4, v66
	v_rcp_f32_e32 v19, v17
	v_div_scale_f32 v16, vcc, v66, v4, v66
	v_fma_f32 v20, -v17, v19, 1.0
	v_fmac_f32_e32 v19, v20, v19
	v_mul_f32_e32 v20, v16, v19
	v_fma_f32 v21, -v17, v20, v16
	v_fmac_f32_e32 v20, v21, v19
	v_fma_f32 v16, -v17, v20, v16
	v_div_fmas_f32 v16, v16, v19, v20
	v_div_fixup_f32 v4, v16, v4, v66
	ds_write_b32 v7, v4
	v_mul_f32_e32 v16, 0xbfb8aa3b, v67
	v_exp_f32_e32 v19, v16
	s_nop 0
	v_add_f32_e32 v4, 1.0, v19
	v_div_scale_f32 v17, s[28:29], v4, v4, v67
	v_rcp_f32_e32 v19, v17
	v_div_scale_f32 v16, vcc, v67, v4, v67
	v_fma_f32 v20, -v17, v19, 1.0
	v_fmac_f32_e32 v19, v20, v19
	v_mul_f32_e32 v20, v16, v19
	v_fma_f32 v21, -v17, v20, v16
	v_fmac_f32_e32 v20, v21, v19
	v_fma_f32 v16, -v17, v20, v16
	v_div_fmas_f32 v16, v16, v19, v20
	v_div_fixup_f32 v4, v16, v4, v67
	ds_write_b32 v7, v4 offset:1024
	v_mul_f32_e32 v16, 0xbfb8aa3b, v68
	v_exp_f32_e32 v19, v16
	s_nop 0
	v_add_f32_e32 v4, 1.0, v19
	v_div_scale_f32 v17, s[28:29], v4, v4, v68
	v_rcp_f32_e32 v19, v17
	v_div_scale_f32 v16, vcc, v68, v4, v68
	v_fma_f32 v20, -v17, v19, 1.0
	v_fmac_f32_e32 v19, v20, v19
	v_mul_f32_e32 v20, v16, v19
	v_fma_f32 v21, -v17, v20, v16
	v_fmac_f32_e32 v20, v21, v19
	v_fma_f32 v16, -v17, v20, v16
	v_div_fmas_f32 v16, v16, v19, v20
	v_div_fixup_f32 v4, v16, v4, v68
	ds_write_b32 v7, v4 offset:2048
	v_mul_f32_e32 v16, 0xbfb8aa3b, v69
	v_exp_f32_e32 v19, v16
	s_nop 0
	v_add_f32_e32 v4, 1.0, v19
	v_div_scale_f32 v17, s[28:29], v4, v4, v69
	v_rcp_f32_e32 v19, v17
	v_div_scale_f32 v16, vcc, v69, v4, v69
	v_fma_f32 v20, -v17, v19, 1.0
	v_fmac_f32_e32 v19, v20, v19
	v_mul_f32_e32 v20, v16, v19
	v_fma_f32 v21, -v17, v20, v16
	v_fmac_f32_e32 v20, v21, v19
	v_fma_f32 v16, -v17, v20, v16
	v_div_fmas_f32 v16, v16, v19, v20
	v_div_fixup_f32 v4, v16, v4, v69
	ds_write_b32 v7, v4 offset:3072
	v_mul_f32_e32 v16, 0xbfb8aa3b, v70
	v_exp_f32_e32 v19, v16
	s_nop 0
	v_add_f32_e32 v4, 1.0, v19
	v_div_scale_f32 v17, s[28:29], v4, v4, v70
	v_rcp_f32_e32 v19, v17
	v_div_scale_f32 v16, vcc, v70, v4, v70
	v_fma_f32 v20, -v17, v19, 1.0
	v_fmac_f32_e32 v19, v20, v19
	v_mul_f32_e32 v20, v16, v19
	v_fma_f32 v21, -v17, v20, v16
	v_fmac_f32_e32 v20, v21, v19
	v_fma_f32 v16, -v17, v20, v16
	v_div_fmas_f32 v16, v16, v19, v20
	v_div_fixup_f32 v4, v16, v4, v70
	ds_write_b32 v7, v4 offset:4096
	v_mul_f32_e32 v16, 0xbfb8aa3b, v71
	v_exp_f32_e32 v19, v16
	s_nop 0
	v_add_f32_e32 v4, 1.0, v19
	v_div_scale_f32 v17, s[28:29], v4, v4, v71
	v_rcp_f32_e32 v19, v17
	v_div_scale_f32 v16, vcc, v71, v4, v71
	v_fma_f32 v20, -v17, v19, 1.0
	v_fmac_f32_e32 v19, v20, v19
	v_mul_f32_e32 v20, v16, v19
	v_fma_f32 v21, -v17, v20, v16
	v_fmac_f32_e32 v20, v21, v19
	v_fma_f32 v16, -v17, v20, v16
	v_div_fmas_f32 v16, v16, v19, v20
	v_div_fixup_f32 v4, v16, v4, v71
	ds_write_b32 v7, v4 offset:5120
	v_mul_f32_e32 v16, 0xbfb8aa3b, v72
	v_exp_f32_e32 v19, v16
	s_nop 0
	v_add_f32_e32 v4, 1.0, v19
	v_div_scale_f32 v17, s[28:29], v4, v4, v72
	v_rcp_f32_e32 v19, v17
	v_div_scale_f32 v16, vcc, v72, v4, v72
	v_fma_f32 v20, -v17, v19, 1.0
	v_fmac_f32_e32 v19, v20, v19
	v_mul_f32_e32 v20, v16, v19
	v_fma_f32 v21, -v17, v20, v16
	v_fmac_f32_e32 v20, v21, v19
	v_fma_f32 v16, -v17, v20, v16
	v_div_fmas_f32 v16, v16, v19, v20
	v_div_fixup_f32 v4, v16, v4, v72
	ds_write_b32 v7, v4 offset:6144
	v_mul_f32_e32 v16, 0xbfb8aa3b, v73
	v_exp_f32_e32 v19, v16
	s_nop 0
	v_add_f32_e32 v4, 1.0, v19
	v_div_scale_f32 v17, s[28:29], v4, v4, v73
	v_rcp_f32_e32 v19, v17
	v_div_scale_f32 v16, vcc, v73, v4, v73
	v_fma_f32 v20, -v17, v19, 1.0
	v_fmac_f32_e32 v19, v20, v19
	v_mul_f32_e32 v20, v16, v19
	v_fma_f32 v21, -v17, v20, v16
	v_fmac_f32_e32 v20, v21, v19
	v_fma_f32 v16, -v17, v20, v16
	v_div_fmas_f32 v16, v16, v19, v20
	v_div_fixup_f32 v4, v16, v4, v73
	ds_write_b32 v7, v4 offset:7168
	v_mul_f32_e32 v16, 0xbfb8aa3b, v74
	v_exp_f32_e32 v19, v16
	s_nop 0
	v_add_f32_e32 v4, 1.0, v19
	v_div_scale_f32 v17, s[28:29], v4, v4, v74
	v_rcp_f32_e32 v19, v17
	v_div_scale_f32 v16, vcc, v74, v4, v74
	v_fma_f32 v20, -v17, v19, 1.0
	v_fmac_f32_e32 v19, v20, v19
	v_mul_f32_e32 v20, v16, v19
	v_fma_f32 v21, -v17, v20, v16
	v_fmac_f32_e32 v20, v21, v19
	v_fma_f32 v16, -v17, v20, v16
	v_div_fmas_f32 v16, v16, v19, v20
	v_div_fixup_f32 v4, v16, v4, v74
	ds_write_b32 v7, v4 offset:8192
	v_mul_f32_e32 v16, 0xbfb8aa3b, v75
	v_exp_f32_e32 v19, v16
	s_nop 0
	v_add_f32_e32 v4, 1.0, v19
	v_div_scale_f32 v17, s[28:29], v4, v4, v75
	v_rcp_f32_e32 v19, v17
	v_div_scale_f32 v16, vcc, v75, v4, v75
	v_fma_f32 v20, -v17, v19, 1.0
	v_fmac_f32_e32 v19, v20, v19
	v_mul_f32_e32 v20, v16, v19
	v_fma_f32 v21, -v17, v20, v16
	v_fmac_f32_e32 v20, v21, v19
	v_fma_f32 v16, -v17, v20, v16
	v_div_fmas_f32 v16, v16, v19, v20
	v_div_fixup_f32 v4, v16, v4, v75
	ds_write_b32 v7, v4 offset:9216
	v_mul_f32_e32 v16, 0xbfb8aa3b, v76
	v_exp_f32_e32 v19, v16
	s_nop 0
	v_add_f32_e32 v4, 1.0, v19
	v_div_scale_f32 v17, s[28:29], v4, v4, v76
	v_rcp_f32_e32 v19, v17
	v_div_scale_f32 v16, vcc, v76, v4, v76
	v_fma_f32 v20, -v17, v19, 1.0
	v_fmac_f32_e32 v19, v20, v19
	v_mul_f32_e32 v20, v16, v19
	v_fma_f32 v21, -v17, v20, v16
	v_fmac_f32_e32 v20, v21, v19
	v_fma_f32 v16, -v17, v20, v16
	v_div_fmas_f32 v16, v16, v19, v20
	v_div_fixup_f32 v4, v16, v4, v76
	ds_write_b32 v7, v4 offset:10240
	v_mul_f32_e32 v16, 0xbfb8aa3b, v77
	v_exp_f32_e32 v19, v16
	s_nop 0
	v_add_f32_e32 v4, 1.0, v19
	v_div_scale_f32 v17, s[28:29], v4, v4, v77
	v_rcp_f32_e32 v19, v17
	v_div_scale_f32 v16, vcc, v77, v4, v77
	v_fma_f32 v20, -v17, v19, 1.0
	v_fmac_f32_e32 v19, v20, v19
	v_mul_f32_e32 v20, v16, v19
	v_fma_f32 v21, -v17, v20, v16
	v_fmac_f32_e32 v20, v21, v19
	v_fma_f32 v16, -v17, v20, v16
	v_div_fmas_f32 v16, v16, v19, v20
	v_div_fixup_f32 v4, v16, v4, v77
	ds_write_b32 v7, v4 offset:11264
	s_mul_hi_i32 s28, s33, 0x2aaaaaab
	s_waitcnt lgkmcnt(0)
	s_barrier
; __device__ __forceinline__ void ada_item(const Params& p, int it, unsigned char* smem) {
;     ...
;   const float* w = p.w_ada + (size_t)l * 1024 * 6144 + jc * 64 + lane;
;   float a0 = 0.f, a1 = 0.f, a2 = 0.f;
;   const int kb = wid * 256;
; #pragma unroll 8
;   for (int k = 0; k < 256; ++k) {
;     const float wv = __builtin_nontemporal_load(w + (size_t)(kb + k) * 6144);
;     a0 += sc[kb + k] * wv;
;     a1 += sc[1024 + kb + k] * wv;
;     a2 += sc[2048 + kb + k] * wv;
;   }
	global_load_dwordx2 v[10:11], v[2:3], off offset:32
	s_lshr_b32 s29, s28, 31
	s_ashr_i32 s54, s28, 4
	s_add_i32 s54, s54, s29
	s_mul_i32 s28, s54, 0x60
	s_sub_i32 s28, s33, s28
	s_lshl_b32 s28, s28, 6
	s_ashr_i32 s29, s28, 31
	s_mul_i32 s58, s54, 0x1800000
	s_lshl_b64 s[56:57], s[28:29], 2
	s_mul_hi_i32 s55, s54, 0x1800000
	s_add_u32 s56, s56, s58
	v_ashrrev_i32_e32 v4, 6, v6
	s_addc_u32 s57, s57, s55
	v_lshlrev_b32_e32 v12, 8, v4
	v_mov_b64_e32 v[16:17], s[56:57]
	v_and_b32_e32 v7, 63, v6
	v_mad_i64_i32 v[16:17], s[56:57], v12, s45, v[16:17]
	v_lshl_or_b32 v16, v7, 2, v16
	v_mov_b32_e32 v13, 0
	v_mov_b32_e32 v8, 0
	v_lshlrev_b32_e32 v14, 10, v4
	v_mov_b32_e32 v9, v5
	s_waitcnt vmcnt(0) lgkmcnt(0)
	v_lshl_add_u64 v[10:11], v[10:11], 0, v[16:17]
	v_lshlrev_b32_e32 v170, 2, v7
	v_add_u32_e32 v171, 0x6000, v170
	v_add_u32_e32 v172, 0xc000, v170
	v_add_u32_e32 v173, 0x12000, v170
	v_add_u32_e32 v174, 0x18000, v170
	v_add_u32_e32 v175, 0x1e000, v170
	v_add_u32_e32 v176, 0x24000, v170
	v_add_u32_e32 v177, 0x2a000, v170
	v_readfirstlane_b32 s68, v10
	v_readfirstlane_b32 s69, v11
	s_nop 4
	global_load_dword v106, v170, s[68:69] nt
	global_load_dword v108, v171, s[68:69] nt
	global_load_dword v110, v172, s[68:69] nt
	global_load_dword v112, v173, s[68:69] nt
	global_load_dword v114, v174, s[68:69] nt
	global_load_dword v116, v175, s[68:69] nt
	global_load_dword v118, v176, s[68:69] nt
	global_load_dword v120, v177, s[68:69] nt
	s_add_u32 s68, s68, 0x30000
	s_addc_u32 s69, s69, 0
	global_load_dword v122, v170, s[68:69] nt
	global_load_dword v124, v171, s[68:69] nt
	global_load_dword v126, v172, s[68:69] nt
	global_load_dword v128, v173, s[68:69] nt
	global_load_dword v130, v174, s[68:69] nt
	global_load_dword v132, v175, s[68:69] nt
	global_load_dword v134, v176, s[68:69] nt
	global_load_dword v136, v177, s[68:69] nt
	s_add_u32 s68, s68, 0x30000
	s_addc_u32 s69, s69, 0
	global_load_dword v138, v170, s[68:69] nt
	global_load_dword v140, v171, s[68:69] nt
	global_load_dword v142, v172, s[68:69] nt
	global_load_dword v144, v173, s[68:69] nt
	global_load_dword v146, v174, s[68:69] nt
	global_load_dword v148, v175, s[68:69] nt
	global_load_dword v150, v176, s[68:69] nt
	global_load_dword v152, v177, s[68:69] nt
	s_add_u32 s68, s68, 0x30000
	s_addc_u32 s69, s69, 0
	s_mov_b32 s70, 7
.Lada_loop:
	global_load_dword v154, v170, s[68:69] nt
	global_load_dword v156, v171, s[68:69] nt
	global_load_dword v158, v172, s[68:69] nt
	global_load_dword v160, v173, s[68:69] nt
	global_load_dword v162, v174, s[68:69] nt
	global_load_dword v164, v175, s[68:69] nt
	global_load_dword v166, v176, s[68:69] nt
	global_load_dword v168, v177, s[68:69] nt
	s_add_u32 s68, s68, 0x30000
	s_addc_u32 s69, s69, 0
	ds_read_b128 v[16:19], v14
	ds_read_b128 v[20:23], v14 offset:16
	ds_read_b128 v[24:27], v14 offset:4096
	ds_read_b128 v[28:31], v14 offset:4112
	ds_read_b128 v[32:35], v14 offset:8192
	ds_read_b128 v[36:39], v14 offset:8208
	s_waitcnt lgkmcnt(0)
	v_mov_b32_e32 v56, v16
	v_mov_b32_e32 v57, v24
	v_mov_b32_e32 v24, v17
	v_mov_b32_e32 v16, v18
	v_mov_b32_e32 v17, v26
	v_mov_b32_e32 v26, v19
	v_mov_b32_e32 v18, v20
	v_mov_b32_e32 v19, v28
	v_mov_b32_e32 v28, v21
	v_mov_b32_e32 v20, v22
	v_mov_b32_e32 v21, v30
	v_mov_b32_e32 v30, v23
	v_add_u32_e32 v14, 32, v14
	s_waitcnt vmcnt(24)
	v_pk_fma_f32 v[8:9], v[106:107], v[56:57], v[8:9] op_sel_hi:[0,1,1]
	v_fmac_f32_e32 v13, v106, v32
	v_pk_fma_f32 v[8:9], v[108:109], v[24:25], v[8:9] op_sel_hi:[0,1,1]
	v_fmac_f32_e32 v13, v108, v33
	v_pk_fma_f32 v[8:9], v[110:111], v[16:17], v[8:9] op_sel_hi:[0,1,1]
	v_fmac_f32_e32 v13, v110, v34
	v_pk_fma_f32 v[8:9], v[112:113], v[26:27], v[8:9] op_sel_hi:[0,1,1]
	v_fmac_f32_e32 v13, v112, v35
	v_pk_fma_f32 v[8:9], v[114:115], v[18:19], v[8:9] op_sel_hi:[0,1,1]
	v_fmac_f32_e32 v13, v114, v36
	v_pk_fma_f32 v[8:9], v[116:117], v[28:29], v[8:9] op_sel_hi:[0,1,1]
	v_fmac_f32_e32 v13, v116, v37
	v_pk_fma_f32 v[8:9], v[118:119], v[20:21], v[8:9] op_sel_hi:[0,1,1]
	v_fmac_f32_e32 v13, v118, v38
	v_pk_fma_f32 v[8:9], v[120:121], v[30:31], v[8:9] op_sel_hi:[0,1,1]
	v_fmac_f32_e32 v13, v120, v39
	global_load_dword v106, v170, s[68:69] nt
	global_load_dword v108, v171, s[68:69] nt
	global_load_dword v110, v172, s[68:69] nt
	global_load_dword v112, v173, s[68:69] nt
	global_load_dword v114, v174, s[68:69] nt
	global_load_dword v116, v175, s[68:69] nt
	global_load_dword v118, v176, s[68:69] nt
	global_load_dword v120, v177, s[68:69] nt
	s_add_u32 s68, s68, 0x30000
	s_addc_u32 s69, s69, 0
	ds_read_b128 v[16:19], v14
	ds_read_b128 v[20:23], v14 offset:16
	ds_read_b128 v[24:27], v14 offset:4096
	ds_read_b128 v[28:31], v14 offset:4112
	ds_read_b128 v[32:35], v14 offset:8192
	ds_read_b128 v[36:39], v14 offset:8208
	s_waitcnt lgkmcnt(0)
	v_mov_b32_e32 v56, v16
	v_mov_b32_e32 v57, v24
	v_mov_b32_e32 v24, v17
	v_mov_b32_e32 v16, v18
	v_mov_b32_e32 v17, v26
	v_mov_b32_e32 v26, v19
	v_mov_b32_e32 v18, v20
	v_mov_b32_e32 v19, v28
	v_mov_b32_e32 v28, v21
	v_mov_b32_e32 v20, v22
	v_mov_b32_e32 v21, v30
	v_mov_b32_e32 v30, v23
	v_add_u32_e32 v14, 32, v14
	s_waitcnt vmcnt(24)
; __device__ __forceinline__ void ada_item(const Params& p, int it, unsigned char* smem) {
;     ...
; #pragma unroll 8
;   for (int k = 0; k < 256; ++k) {
;     const float wv = __builtin_nontemporal_load(w + (size_t)(kb + k) * 6144);
;     a0 += sc[kb + k] * wv;
;     a1 += sc[1024 + kb + k] * wv;
;     a2 += sc[2048 + kb + k] * wv;
;   }
	v_pk_fma_f32 v[8:9], v[122:123], v[56:57], v[8:9] op_sel_hi:[0,1,1]
	v_fmac_f32_e32 v13, v122, v32
	v_pk_fma_f32 v[8:9], v[124:125], v[24:25], v[8:9] op_sel_hi:[0,1,1]
	v_fmac_f32_e32 v13, v124, v33
	v_pk_fma_f32 v[8:9], v[126:127], v[16:17], v[8:9] op_sel_hi:[0,1,1]
	v_fmac_f32_e32 v13, v126, v34
	v_pk_fma_f32 v[8:9], v[128:129], v[26:27], v[8:9] op_sel_hi:[0,1,1]
	v_fmac_f32_e32 v13, v128, v35
	v_pk_fma_f32 v[8:9], v[130:131], v[18:19], v[8:9] op_sel_hi:[0,1,1]
	v_fmac_f32_e32 v13, v130, v36
	v_pk_fma_f32 v[8:9], v[132:133], v[28:29], v[8:9] op_sel_hi:[0,1,1]
	v_fmac_f32_e32 v13, v132, v37
	v_pk_fma_f32 v[8:9], v[134:135], v[20:21], v[8:9] op_sel_hi:[0,1,1]
	v_fmac_f32_e32 v13, v134, v38
	v_pk_fma_f32 v[8:9], v[136:137], v[30:31], v[8:9] op_sel_hi:[0,1,1]
	v_fmac_f32_e32 v13, v136, v39
	global_load_dword v122, v170, s[68:69] nt
	global_load_dword v124, v171, s[68:69] nt
	global_load_dword v126, v172, s[68:69] nt
	global_load_dword v128, v173, s[68:69] nt
	global_load_dword v130, v174, s[68:69] nt
	global_load_dword v132, v175, s[68:69] nt
	global_load_dword v134, v176, s[68:69] nt
	global_load_dword v136, v177, s[68:69] nt
	s_add_u32 s68, s68, 0x30000
	s_addc_u32 s69, s69, 0
	ds_read_b128 v[16:19], v14
	ds_read_b128 v[20:23], v14 offset:16
	ds_read_b128 v[24:27], v14 offset:4096
	ds_read_b128 v[28:31], v14 offset:4112
	ds_read_b128 v[32:35], v14 offset:8192
	ds_read_b128 v[36:39], v14 offset:8208
	s_waitcnt lgkmcnt(0)
	v_mov_b32_e32 v56, v16
	v_mov_b32_e32 v57, v24
	v_mov_b32_e32 v24, v17
	v_mov_b32_e32 v16, v18
	v_mov_b32_e32 v17, v26
	v_mov_b32_e32 v26, v19
	v_mov_b32_e32 v18, v20
	v_mov_b32_e32 v19, v28
	v_mov_b32_e32 v28, v21
	v_mov_b32_e32 v20, v22
	v_mov_b32_e32 v21, v30
	v_mov_b32_e32 v30, v23
	v_add_u32_e32 v14, 32, v14
	s_waitcnt vmcnt(24)
	v_pk_fma_f32 v[8:9], v[138:139], v[56:57], v[8:9] op_sel_hi:[0,1,1]
	v_fmac_f32_e32 v13, v138, v32
	v_pk_fma_f32 v[8:9], v[140:141], v[24:25], v[8:9] op_sel_hi:[0,1,1]
	v_fmac_f32_e32 v13, v140, v33
	v_pk_fma_f32 v[8:9], v[142:143], v[16:17], v[8:9] op_sel_hi:[0,1,1]
	v_fmac_f32_e32 v13, v142, v34
	v_pk_fma_f32 v[8:9], v[144:145], v[26:27], v[8:9] op_sel_hi:[0,1,1]
	v_fmac_f32_e32 v13, v144, v35
	v_pk_fma_f32 v[8:9], v[146:147], v[18:19], v[8:9] op_sel_hi:[0,1,1]
	v_fmac_f32_e32 v13, v146, v36
	v_pk_fma_f32 v[8:9], v[148:149], v[28:29], v[8:9] op_sel_hi:[0,1,1]
	v_fmac_f32_e32 v13, v148, v37
	v_pk_fma_f32 v[8:9], v[150:151], v[20:21], v[8:9] op_sel_hi:[0,1,1]
	v_fmac_f32_e32 v13, v150, v38
	v_pk_fma_f32 v[8:9], v[152:153], v[30:31], v[8:9] op_sel_hi:[0,1,1]
	v_fmac_f32_e32 v13, v152, v39
	global_load_dword v138, v170, s[68:69] nt
	global_load_dword v140, v171, s[68:69] nt
	global_load_dword v142, v172, s[68:69] nt
	global_load_dword v144, v173, s[68:69] nt
	global_load_dword v146, v174, s[68:69] nt
	global_load_dword v148, v175, s[68:69] nt
	global_load_dword v150, v176, s[68:69] nt
	global_load_dword v152, v177, s[68:69] nt
	s_add_u32 s68, s68, 0x30000
	s_addc_u32 s69, s69, 0
	ds_read_b128 v[16:19], v14
	ds_read_b128 v[20:23], v14 offset:16
	ds_read_b128 v[24:27], v14 offset:4096
	ds_read_b128 v[28:31], v14 offset:4112
	ds_read_b128 v[32:35], v14 offset:8192
	ds_read_b128 v[36:39], v14 offset:8208
	s_waitcnt lgkmcnt(0)
	v_mov_b32_e32 v56, v16
	v_mov_b32_e32 v57, v24
	v_mov_b32_e32 v24, v17
	v_mov_b32_e32 v16, v18
	v_mov_b32_e32 v17, v26
	v_mov_b32_e32 v26, v19
	v_mov_b32_e32 v18, v20
	v_mov_b32_e32 v19, v28
	v_mov_b32_e32 v28, v21
	v_mov_b32_e32 v20, v22
	v_mov_b32_e32 v21, v30
	v_mov_b32_e32 v30, v23
	v_add_u32_e32 v14, 32, v14
	s_waitcnt vmcnt(24)
	v_pk_fma_f32 v[8:9], v[154:155], v[56:57], v[8:9] op_sel_hi:[0,1,1]
	v_fmac_f32_e32 v13, v154, v32
	v_pk_fma_f32 v[8:9], v[156:157], v[24:25], v[8:9] op_sel_hi:[0,1,1]
	v_fmac_f32_e32 v13, v156, v33
	v_pk_fma_f32 v[8:9], v[158:159], v[16:17], v[8:9] op_sel_hi:[0,1,1]
	v_fmac_f32_e32 v13, v158, v34
	v_pk_fma_f32 v[8:9], v[160:161], v[26:27], v[8:9] op_sel_hi:[0,1,1]
	v_fmac_f32_e32 v13, v160, v35
	v_pk_fma_f32 v[8:9], v[162:163], v[18:19], v[8:9] op_sel_hi:[0,1,1]
	v_fmac_f32_e32 v13, v162, v36
	v_pk_fma_f32 v[8:9], v[164:165], v[28:29], v[8:9] op_sel_hi:[0,1,1]
	v_fmac_f32_e32 v13, v164, v37
	v_pk_fma_f32 v[8:9], v[166:167], v[20:21], v[8:9] op_sel_hi:[0,1,1]
	v_fmac_f32_e32 v13, v166, v38
	v_pk_fma_f32 v[8:9], v[168:169], v[30:31], v[8:9] op_sel_hi:[0,1,1]
	v_fmac_f32_e32 v13, v168, v39
	s_sub_i32 s70, s70, 1
	s_cmp_lg_u32 s70, 0
	s_cbranch_scc1 .Lada_loop
; __device__ __forceinline__ void ada_item(const Params& p, int it, unsigned char* smem) {
;     ...
; #pragma unroll 8
;   for (int k = 0; k < 256; ++k) {
;     const float wv = __builtin_nontemporal_load(w + (size_t)(kb + k) * 6144);
;     a0 += sc[kb + k] * wv;
;     a1 += sc[1024 + kb + k] * wv;
;     a2 += sc[2048 + kb + k] * wv;
;   }
;   red[(wid * 3 + 0) * 64 + lane] = a0;
;   red[(wid * 3 + 1) * 64 + lane] = a1;
;   red[(wid * 3 + 2) * 64 + lane] = a2;
;   __syncthreads();
	global_load_dword v154, v170, s[68:69] nt
	global_load_dword v156, v171, s[68:69] nt
	global_load_dword v158, v172, s[68:69] nt
	global_load_dword v160, v173, s[68:69] nt
	global_load_dword v162, v174, s[68:69] nt
	global_load_dword v164, v175, s[68:69] nt
	global_load_dword v166, v176, s[68:69] nt
	global_load_dword v168, v177, s[68:69] nt
	s_add_u32 s68, s68, 0x30000
	s_addc_u32 s69, s69, 0
	ds_read_b128 v[16:19], v14
	ds_read_b128 v[20:23], v14 offset:16
	ds_read_b128 v[24:27], v14 offset:4096
	ds_read_b128 v[28:31], v14 offset:4112
	ds_read_b128 v[32:35], v14 offset:8192
	ds_read_b128 v[36:39], v14 offset:8208
	s_waitcnt lgkmcnt(0)
	v_mov_b32_e32 v56, v16
	v_mov_b32_e32 v57, v24
	v_mov_b32_e32 v24, v17
	v_mov_b32_e32 v16, v18
	v_mov_b32_e32 v17, v26
	v_mov_b32_e32 v26, v19
	v_mov_b32_e32 v18, v20
	v_mov_b32_e32 v19, v28
	v_mov_b32_e32 v28, v21
	v_mov_b32_e32 v20, v22
	v_mov_b32_e32 v21, v30
	v_mov_b32_e32 v30, v23
	v_add_u32_e32 v14, 32, v14
	s_waitcnt vmcnt(24)
	v_pk_fma_f32 v[8:9], v[106:107], v[56:57], v[8:9] op_sel_hi:[0,1,1]
	v_fmac_f32_e32 v13, v106, v32
	v_pk_fma_f32 v[8:9], v[108:109], v[24:25], v[8:9] op_sel_hi:[0,1,1]
	v_fmac_f32_e32 v13, v108, v33
	v_pk_fma_f32 v[8:9], v[110:111], v[16:17], v[8:9] op_sel_hi:[0,1,1]
	v_fmac_f32_e32 v13, v110, v34
	v_pk_fma_f32 v[8:9], v[112:113], v[26:27], v[8:9] op_sel_hi:[0,1,1]
	v_fmac_f32_e32 v13, v112, v35
	v_pk_fma_f32 v[8:9], v[114:115], v[18:19], v[8:9] op_sel_hi:[0,1,1]
	v_fmac_f32_e32 v13, v114, v36
	v_pk_fma_f32 v[8:9], v[116:117], v[28:29], v[8:9] op_sel_hi:[0,1,1]
	v_fmac_f32_e32 v13, v116, v37
	v_pk_fma_f32 v[8:9], v[118:119], v[20:21], v[8:9] op_sel_hi:[0,1,1]
	v_fmac_f32_e32 v13, v118, v38
	v_pk_fma_f32 v[8:9], v[120:121], v[30:31], v[8:9] op_sel_hi:[0,1,1]
	v_fmac_f32_e32 v13, v120, v39
	ds_read_b128 v[16:19], v14
	ds_read_b128 v[20:23], v14 offset:16
	ds_read_b128 v[24:27], v14 offset:4096
	ds_read_b128 v[28:31], v14 offset:4112
	ds_read_b128 v[32:35], v14 offset:8192
	ds_read_b128 v[36:39], v14 offset:8208
	s_waitcnt lgkmcnt(0)
	v_mov_b32_e32 v56, v16
	v_mov_b32_e32 v57, v24
	v_mov_b32_e32 v24, v17
	v_mov_b32_e32 v16, v18
	v_mov_b32_e32 v17, v26
	v_mov_b32_e32 v26, v19
	v_mov_b32_e32 v18, v20
	v_mov_b32_e32 v19, v28
	v_mov_b32_e32 v28, v21
	v_mov_b32_e32 v20, v22
	v_mov_b32_e32 v21, v30
	v_mov_b32_e32 v30, v23
	v_add_u32_e32 v14, 32, v14
	s_waitcnt vmcnt(16)
	v_pk_fma_f32 v[8:9], v[122:123], v[56:57], v[8:9] op_sel_hi:[0,1,1]
	v_fmac_f32_e32 v13, v122, v32
	v_pk_fma_f32 v[8:9], v[124:125], v[24:25], v[8:9] op_sel_hi:[0,1,1]
	v_fmac_f32_e32 v13, v124, v33
	v_pk_fma_f32 v[8:9], v[126:127], v[16:17], v[8:9] op_sel_hi:[0,1,1]
	v_fmac_f32_e32 v13, v126, v34
	v_pk_fma_f32 v[8:9], v[128:129], v[26:27], v[8:9] op_sel_hi:[0,1,1]
	v_fmac_f32_e32 v13, v128, v35
	v_pk_fma_f32 v[8:9], v[130:131], v[18:19], v[8:9] op_sel_hi:[0,1,1]
	v_fmac_f32_e32 v13, v130, v36
	v_pk_fma_f32 v[8:9], v[132:133], v[28:29], v[8:9] op_sel_hi:[0,1,1]
	v_fmac_f32_e32 v13, v132, v37
	v_pk_fma_f32 v[8:9], v[134:135], v[20:21], v[8:9] op_sel_hi:[0,1,1]
	v_fmac_f32_e32 v13, v134, v38
	v_pk_fma_f32 v[8:9], v[136:137], v[30:31], v[8:9] op_sel_hi:[0,1,1]
	v_fmac_f32_e32 v13, v136, v39
	ds_read_b128 v[16:19], v14
	ds_read_b128 v[20:23], v14 offset:16
	ds_read_b128 v[24:27], v14 offset:4096
	ds_read_b128 v[28:31], v14 offset:4112
	ds_read_b128 v[32:35], v14 offset:8192
	ds_read_b128 v[36:39], v14 offset:8208
	s_waitcnt lgkmcnt(0)
	v_mov_b32_e32 v56, v16
	v_mov_b32_e32 v57, v24
	v_mov_b32_e32 v24, v17
	v_mov_b32_e32 v16, v18
	v_mov_b32_e32 v17, v26
	v_mov_b32_e32 v26, v19
	v_mov_b32_e32 v18, v20
	v_mov_b32_e32 v19, v28
	v_mov_b32_e32 v28, v21
	v_mov_b32_e32 v20, v22
	v_mov_b32_e32 v21, v30
	v_mov_b32_e32 v30, v23
	v_add_u32_e32 v14, 32, v14
	s_waitcnt vmcnt(8)
	v_pk_fma_f32 v[8:9], v[138:139], v[56:57], v[8:9] op_sel_hi:[0,1,1]
	v_fmac_f32_e32 v13, v138, v32
	v_pk_fma_f32 v[8:9], v[140:141], v[24:25], v[8:9] op_sel_hi:[0,1,1]
	v_fmac_f32_e32 v13, v140, v33
	v_pk_fma_f32 v[8:9], v[142:143], v[16:17], v[8:9] op_sel_hi:[0,1,1]
	v_fmac_f32_e32 v13, v142, v34
	v_pk_fma_f32 v[8:9], v[144:145], v[26:27], v[8:9] op_sel_hi:[0,1,1]
	v_fmac_f32_e32 v13, v144, v35
	v_pk_fma_f32 v[8:9], v[146:147], v[18:19], v[8:9] op_sel_hi:[0,1,1]
	v_fmac_f32_e32 v13, v146, v36
	v_pk_fma_f32 v[8:9], v[148:149], v[28:29], v[8:9] op_sel_hi:[0,1,1]
	v_fmac_f32_e32 v13, v148, v37
	v_pk_fma_f32 v[8:9], v[150:151], v[20:21], v[8:9] op_sel_hi:[0,1,1]
	v_fmac_f32_e32 v13, v150, v38
	v_pk_fma_f32 v[8:9], v[152:153], v[30:31], v[8:9] op_sel_hi:[0,1,1]
	v_fmac_f32_e32 v13, v152, v39
	ds_read_b128 v[16:19], v14
	ds_read_b128 v[20:23], v14 offset:16
	ds_read_b128 v[24:27], v14 offset:4096
	ds_read_b128 v[28:31], v14 offset:4112
	ds_read_b128 v[32:35], v14 offset:8192
	ds_read_b128 v[36:39], v14 offset:8208
	s_waitcnt lgkmcnt(0)
	v_mov_b32_e32 v56, v16
	v_mov_b32_e32 v57, v24
	v_mov_b32_e32 v24, v17
	v_mov_b32_e32 v16, v18
	v_mov_b32_e32 v17, v26
	v_mov_b32_e32 v26, v19
	v_mov_b32_e32 v18, v20
	v_mov_b32_e32 v19, v28
	v_mov_b32_e32 v28, v21
	v_mov_b32_e32 v20, v22
	v_mov_b32_e32 v21, v30
	v_mov_b32_e32 v30, v23
	v_add_u32_e32 v14, 32, v14
	s_waitcnt vmcnt(0)
	v_pk_fma_f32 v[8:9], v[154:155], v[56:57], v[8:9] op_sel_hi:[0,1,1]
	v_fmac_f32_e32 v13, v154, v32
	v_pk_fma_f32 v[8:9], v[156:157], v[24:25], v[8:9] op_sel_hi:[0,1,1]
	v_fmac_f32_e32 v13, v156, v33
	v_pk_fma_f32 v[8:9], v[158:159], v[16:17], v[8:9] op_sel_hi:[0,1,1]
	v_fmac_f32_e32 v13, v158, v34
	v_pk_fma_f32 v[8:9], v[160:161], v[26:27], v[8:9] op_sel_hi:[0,1,1]
	v_fmac_f32_e32 v13, v160, v35
	v_pk_fma_f32 v[8:9], v[162:163], v[18:19], v[8:9] op_sel_hi:[0,1,1]
	v_fmac_f32_e32 v13, v162, v36
	v_pk_fma_f32 v[8:9], v[164:165], v[28:29], v[8:9] op_sel_hi:[0,1,1]
	v_fmac_f32_e32 v13, v164, v37
	v_pk_fma_f32 v[8:9], v[166:167], v[20:21], v[8:9] op_sel_hi:[0,1,1]
	v_fmac_f32_e32 v13, v166, v38
	v_pk_fma_f32 v[8:9], v[168:169], v[30:31], v[8:9] op_sel_hi:[0,1,1]
	v_fmac_f32_e32 v13, v168, v39
	v_mul_lo_u32 v10, v4, s39
	v_lshl_or_b32 v10, v7, 2, v10
	v_cmp_gt_i32_e32 vcc, s52, v6
	ds_write2st64_b32 v10, v8, v9 offset0:48 offset1:49
	ds_write_b32 v10, v13 offset:12800
	s_waitcnt lgkmcnt(0)
	s_barrier
; __device__ __forceinline__ void ada_item(const Params& p, int it, unsigned char* smem) {
;     ...
;   if (t < 192) {
;     const int r = t >> 6, ln = t & 63;
;     float s = 0.f;
; #pragma unroll
;     for (int w4 = 0; w4 < 4; ++w4) s += red[(w4 * 3 + r) * 64 + ln];
;     s += p.b_ada[l * 6144 + jc * 64 + ln];
;     p.mada[(l * 3 + r) * 6144 + jc * 64 + ln] = s;
;   }
	s_and_saveexec_b64 s[30:31], vcc
	s_cbranch_execz .LBB0_12
	global_load_dwordx2 v[8:9], v[2:3], off offset:40
	global_load_dwordx2 v[10:11], v[2:3], off offset:184
	s_mul_i32 s29, s54, 0x1800
	s_add_i32 s29, s29, s28
	v_or_b32_e32 v14, s29, v7
	v_ashrrev_i32_e32 v15, 31, v14
	s_waitcnt vmcnt(0) lgkmcnt(0)
	v_lshl_add_u64 v[8:9], v[14:15], 2, v[8:9]
	global_load_dword v16, v[8:9], off
	v_lshl_add_u32 v14, v7, 2, v12
	ds_read2st64_b32 v[12:13], v14 offset0:48 offset1:51
	ds_read2st64_b32 v[14:15], v14 offset0:54 offset1:57
	v_mad_u64_u32 v[8:9], s[54:55], s54, 3, v[4:5]
	v_mul_lo_u32 v4, v8, s53
	v_add_u32_e32 v4, s28, v4
	v_or_b32_e32 v8, v4, v7
	s_waitcnt lgkmcnt(0)
	v_add_f32_e32 v4, 0, v12
	v_add_f32_e32 v4, v4, v13
	v_add_f32_e32 v4, v4, v14
	v_ashrrev_i32_e32 v9, 31, v8
	v_add_f32_e32 v4, v4, v15
	v_lshl_add_u64 v[8:9], v[8:9], 2, v[10:11]
	s_waitcnt vmcnt(0)
	v_add_f32_e32 v4, v4, v16
	global_store_dword v[8:9], v4, off

; __device__ __forceinline__ void conv_item(const Params& p, int it, unsigned char* smem) {
;   const int l = it / 6720;
;   int r = it % 6720;
;   if (r < 240) {
;     const int ct = r >> 4, kt = r & 15;
;     const int c0 = (ct < 8 ? ct : ct + 4) * 64;
;     const int n0 = c0 + (c0 >= 768 ? 256 : 0);
;     convT_tile(p.w_in + (size_t)l * 1024 * 1216, 1216, kt * 64, c0, p.WinT + (size_t)l * 1536 * 1024, 1024, n0, 0, 0, smem);
;     return;
;   }
;   r -= 240;
;   if (r < 48) {
;     const int ct = r >> 2, kt = r & 3;
;     convT_tile(p.w_uq + (size_t)l * 256 * 768, 768, kt * 64, ct * 64, p.WuqT + (size_t)l * 768 * 256, 256, ct * 64, 0, 0, smem, p.q_lora_norm + l * 256);
;     return;
;   }
;   r -= 48;
;   if (r < 32) {
;     const int ct = r >> 1, kt = r & 1;
;     convT_tile(p.w_ukv + (size_t)l * 128 * 1024, 1024, kt * 64, ct * 64, p.WukvT + (size_t)l * 1024 * 128, 128, ct * 64, 0, 0, smem, p.kv_lora_norm + l * 128);
;     return;
;   }
;   r -= 32;
;   if (r < 256) {
;     const int ct = r >> 4, kt = r & 15;
;     convT_tile(p.w_out + (size_t)l * 1024 * 1024, 1024, kt * 64, ct * 64, p.WoutT + (size_t)l * 1024 * 1024, 1024, ct * 64, 0, 0, smem);
;     return;
;   }
;   r -= 256;
;   if (r < 4096) {
;     const int which = r >> 11, r2 = r & 2047, e = r2 >> 7, r3 = r2 & 127, ct = r3 >> 4, kt = r3 & 15;
;     const float* src = (which ? p.w_up : p.w_gate) + (size_t)(l * 16 + e) * 1024 * 512;
;     convT_tile(src, 512, kt * 64, ct * 64, p.WguT + (size_t)(l * 16 + e) * 1024 * 1024, 1024, 0, 1, which, smem);
;     return;
;   }
;   r -= 4096;
.LBB0_23:
	s_add_i32 s14, s2, 64
	s_and_b32 s14, s14, 0x1ff
	s_addk_i32 s14, 0x3480
	s_cmp_lt_u32 s2, 0x140
	s_cbranch_scc1 .LBB0_62
	s_sub_i32 s14, s2, 0x140
	s_load_dwordx2 s[0:1], s[64:65], 0x1b0
	s_lshl_b32 s15, s14, 6
	s_lshl_b32 s17, s14, 4
	s_lshl_b32 s19, s14, 5
	s_lshl_b32 s21, s14, 2
	s_waitcnt lgkmcnt(0)
	s_mov_b64 s[4:5], s[0:1]
	s_movk_i32 s4, 0xc0
	s_lshl_b32 s0, s14, 3
	s_lshl_b32 s16, s4, 6
	s_lshl_b32 s18, s4, 4
	s_lshl_b32 s20, s4, 5
	s_lshl_b32 s22, s4, 2
	s_add_i32 s23, s0, 0xffff6e00
	s_lshl_b32 s24, s4, 3
	s_mov_b32 s5, 0
	v_mov_b32_e32 v19, 0
	s_mov_b32 s25, 0x10000
	s_mov_b32 s26, 0x20000
	s_mov_b32 s27, 0x30000
	s_movk_i32 s28, 0x104
	s_movk_i32 s29, 0x90
	s_mov_b32 s30, 0x8000
	s_mov_b32 s31, 0x18000
	s_movk_i32 s33, 0xc00
	s_movk_i32 s34, 0x1300
	v_mov_b32_e32 v1, 0xc0000
	v_mov_b32_e32 v25, 0x60000
	v_mov_b32_e32 v27, 0x4c0000
	v_mov_b32_e32 v28, 0x300000
	s_branch .LBB0_26
.LBB0_25:
	s_load_dwordx2 s[0:1], s[64:65], 0x1b0
	s_add_i32 s15, s15, s16
	s_add_i32 s17, s17, s18
	s_add_i32 s19, s19, s20
	s_add_i32 s21, s21, s22
	s_waitcnt lgkmcnt(0)
	s_addk_i32 s14, 0xc0
	s_add_i32 s23, s23, s24
	s_cmpk_lt_i32 s14, 0x3480
	s_cbranch_scc0 .LBB0_62
.LBB0_26:
	s_mul_hi_i32 s0, s14, 0x9c09c09d
	s_add_i32 s0, s0, s14
	s_lshr_b32 s1, s0, 31
	s_ashr_i32 s0, s0, 12
	s_add_i32 s6, s0, s1
	s_mul_i32 s0, s6, 0xffffe5c0
	s_add_i32 s35, s14, s0
	s_cmpk_gt_i32 s35, 0xef
	s_mov_b64 s[0:1], -1
	s_cbranch_scc0 .LBB0_60
	s_cmpk_gt_u32 s35, 0x11f
	s_cbranch_scc0 .LBB0_49
	s_cmpk_gt_u32 s35, 0x13f
	s_cbranch_scc0 .LBB0_38
	s_cmpk_gt_u32 s35, 0x23f
	s_cbranch_scc0 .LBB0_35
	s_cmpk_gt_i32 s14, 0x1a3f
	s_cbranch_scc1 .Lprep_convdone
	s_addk_i32 s14, 0x1800
	s_lshl_b32 s15, s14, 6
	s_lshl_b32 s17, s14, 4
	s_lshl_b32 s19, s14, 5
	s_lshl_b32 s21, s14, 2
	s_lshl_b32 s0, s14, 3
	s_add_i32 s23, s0, 0xffff6e00
	s_branch .LBB0_26
; __device__ __forceinline__ u16 f2bf(float f) { return (u16)(pack2(f, 0.f) & 0xffffu); }
; __device__ __forceinline__ int tid_() { int t = threadIdx.x; asm volatile("" : "+v"(t)); return t; }
; __device__ __forceinline__ void convT_tile(const float* __restrict__ src, int lds, int k0, int c0, u16* __restrict__ dst, int Kd,
;                                            int rbase, int mode, int which, unsigned char* smem, const float* __restrict__ kscale = nullptr) {
;   float* tile = (float*)smem;
;   const int t = tid_();
;   float4 v4[4];
; #pragma unroll
;   for (int i = 0; i < 4; ++i) {
;     const f32x4 w_ = __builtin_nontemporal_load((const f32x4*)(src + (size_t)(k0 + i * 16 + (t >> 4)) * lds + c0 + (t & 15) * 4));
;     v4[i] = make_float4(w_[0], w_[1], w_[2], w_[3]);
;   }
; #pragma unroll
;   for (int i = 0; i < 4; ++i) {
;     const int kk = i * 16 + (t >> 4), cc = (t & 15) * 4;
;     const float sc = kscale ? kscale[k0 + kk] : 1.f;
;     tile[kk * 65 + cc + 0] = v4[i].x * sc; tile[kk * 65 + cc + 1] = v4[i].y * sc;
;     tile[kk * 65 + cc + 2] = v4[i].z * sc; tile[kk * 65 + cc + 3] = v4[i].w * sc;
;   }
;   __syncthreads();
; #pragma unroll
;   for (int i = 0; i < 16; ++i) {
;     const int cc = i * 4 + (t >> 6), kk = t & 63;
;     int row;
;     if (mode == 0) row = rbase + cc;
;     else { const int f = c0 + cc; row = (((f >> 4) * 2 + which) << 4) + (f & 15); }
;     dst[(size_t)row * Kd + k0 + kk] = f2bf(tile[kk * 65 + cc]);
;   }
;   __syncthreads();
; }
; __device__ __forceinline__ void conv_item(const Params& p, int it, unsigned char* smem) {
;     ...
;   {
;     const int e = r >> 7, r3 = r & 127, ct = r3 >> 3, kt = r3 & 7;
;     convT_tile(p.w_down + (size_t)(l * 16 + e) * 512 * 1024, 1024, kt * 64, ct * 64, p.WdT + (size_t)(l * 16 + e) * 1024 * 512, 512, ct * 64, 0, 0, smem);
;   }
.Lprep_convdone:
	s_add_i32 s14, s2, 64
	s_and_b32 s14, s14, 0x1ff
	s_addk_i32 s14, 0x3480
	s_branch .LBB0_62
	s_nop 0
	v_mov_b64_e32 v[2:3], s[10:11]
	global_load_dwordx2 v[4:5], v[2:3], off offset:160
	s_add_i32 s0, s35, 0xffffedc0
	s_lshl_b32 s1, s6, 4
	s_lshl_b32 s4, s6, 9
	s_lshr_b32 s0, s0, 7
	v_mov_b32_e32 v6, v187
	s_sub_i32 s4, s23, s4
	s_add_i32 s0, s0, s1
	global_load_dwordx2 v[2:3], v[2:3], off offset:232
	s_and_b32 s12, s4, 0x3c0
	v_ashrrev_i32_e32 v9, 6, v6
	s_ashr_i32 s1, s0, 31
	s_and_b32 s7, s15, 0x1c0
	v_ashrrev_i32_e32 v8, 4, v6
	s_lshl_b32 s4, s12, 2
	v_add_u32_e32 v16, s12, v9
	s_lshl_b64 s[12:13], s[0:1], 21
	v_lshlrev_b32_e32 v7, 4, v6
	v_and_b32_e32 v24, 63, v6
	v_add_u32_e32 v6, s7, v8
	v_and_b32_e32 v18, 0xf0, v7
	v_ashrrev_i32_e32 v7, 31, v6
	v_lshlrev_b64 v[6:7], 12, v[6:7]
	v_lshlrev_b32_e32 v9, 2, v9
	v_mad_u64_u32 v[30:31], s[36:37], v8, s28, v[18:19]
	v_mad_u32_u24 v26, v24, s28, v9
	v_add_u32_e32 v29, 0x1040, v30
	v_add_u32_e32 v31, 0x1048, v30
	v_add_u32_e32 v62, 0x2080, v30
	v_add_u32_e32 v63, 0x2088, v30
	v_add_u32_e32 v64, 0x30c0, v30
	v_add_u32_e32 v65, 0x30c8, v30
	s_lshl_b64 s[0:1], s[0:1], 20
	v_add_u32_e32 v34, 8, v16
	v_add_u32_e32 v36, 12, v16
	v_add_u32_e32 v38, 16, v16
	v_add_u32_e32 v40, 20, v16
	v_add_u32_e32 v42, 24, v16
	v_add_u32_e32 v44, 28, v16
	v_add_u32_e32 v46, 32, v16
	v_add_u32_e32 v48, 36, v16
	v_add_u32_e32 v50, 40, v16
	v_add_u32_e32 v52, 44, v16
	v_add_u32_e32 v54, 48, v16
	v_add_u32_e32 v56, 52, v16
	v_add_u32_e32 v58, 56, v16
	v_add_u32_e32 v60, 60, v16
	v_ashrrev_i32_e32 v17, 31, v16
	v_ashrrev_i32_e32 v35, 31, v34
	v_ashrrev_i32_e32 v37, 31, v36
	v_ashrrev_i32_e32 v39, 31, v38
	v_ashrrev_i32_e32 v41, 31, v40
	v_ashrrev_i32_e32 v43, 31, v42
	v_ashrrev_i32_e32 v45, 31, v44
	v_ashrrev_i32_e32 v47, 31, v46
	v_ashrrev_i32_e32 v49, 31, v48
	v_ashrrev_i32_e32 v51, 31, v50
	v_ashrrev_i32_e32 v53, 31, v52
	v_ashrrev_i32_e32 v55, 31, v54
	v_ashrrev_i32_e32 v57, 31, v56
	v_ashrrev_i32_e32 v59, 31, v58
	v_ashrrev_i32_e32 v61, 31, v60
	v_lshlrev_b64 v[34:35], 10, v[34:35]
	v_lshlrev_b64 v[36:37], 10, v[36:37]
	v_lshlrev_b64 v[38:39], 10, v[38:39]
	v_lshlrev_b64 v[40:41], 10, v[40:41]
	v_lshlrev_b64 v[42:43], 10, v[42:43]
	v_lshlrev_b64 v[44:45], 10, v[44:45]
	v_lshlrev_b64 v[46:47], 10, v[46:47]
	v_lshlrev_b64 v[48:49], 10, v[48:49]
	v_lshlrev_b64 v[50:51], 10, v[50:51]
	v_lshlrev_b64 v[52:53], 10, v[52:53]
	v_lshlrev_b64 v[54:55], 10, v[54:55]
	v_lshlrev_b64 v[56:57], 10, v[56:57]
	v_lshlrev_b64 v[58:59], 10, v[58:59]
	v_lshlrev_b64 v[60:61], 10, v[60:61]
	s_waitcnt vmcnt(0) lgkmcnt(0)
	v_lshl_add_u64 v[4:5], v[4:5], 0, s[12:13]
	v_lshl_add_u64 v[4:5], v[4:5], 0, s[4:5]
	v_lshl_add_u64 v[4:5], v[4:5], 0, v[18:19]
	v_lshl_add_u64 v[20:21], v[4:5], 0, v[6:7]
	v_add_co_u32_e32 v22, vcc, s25, v20
	s_lshl_b32 s4, s7, 1
	s_nop 0
	v_addc_co_u32_e32 v23, vcc, 0, v21, vcc
	v_add_co_u32_e32 v32, vcc, s26, v20
	v_lshl_add_u64 v[2:3], v[2:3], 0, s[0:1]
	s_nop 0
	v_addc_co_u32_e32 v33, vcc, 0, v21, vcc
	global_load_dwordx4 v[4:7], v[20:21], off nt
	global_load_dwordx4 v[8:11], v[22:23], off nt
	global_load_dwordx4 v[12:15], v[32:33], off nt
	v_add_co_u32_e32 v20, vcc, s27, v20
	v_add_u32_e32 v32, 4, v16
	s_nop 0
	v_addc_co_u32_e32 v21, vcc, 0, v21, vcc
	global_load_dwordx4 v[20:23], v[20:21], off nt
	v_ashrrev_i32_e32 v33, 31, v32
	v_lshl_add_u64 v[2:3], v[2:3], 0, s[4:5]
	v_lshlrev_b32_e32 v18, 1, v24
	v_lshlrev_b64 v[16:17], 10, v[16:17]
	v_lshlrev_b64 v[32:33], 10, v[32:33]
	v_lshl_add_u64 v[2:3], v[2:3], 0, v[18:19]
	v_lshl_add_u64 v[16:17], v[2:3], 0, v[16:17]
	v_lshl_add_u64 v[32:33], v[2:3], 0, v[32:33]
	v_lshl_add_u64 v[34:35], v[2:3], 0, v[34:35]
	v_lshl_add_u64 v[36:37], v[2:3], 0, v[36:37]
	v_lshl_add_u64 v[38:39], v[2:3], 0, v[38:39]
	v_lshl_add_u64 v[40:41], v[2:3], 0, v[40:41]
	v_lshl_add_u64 v[42:43], v[2:3], 0, v[42:43]
	v_lshl_add_u64 v[44:45], v[2:3], 0, v[44:45]
	v_lshl_add_u64 v[46:47], v[2:3], 0, v[46:47]
	v_lshl_add_u64 v[48:49], v[2:3], 0, v[48:49]
	v_lshl_add_u64 v[50:51], v[2:3], 0, v[50:51]
	v_lshl_add_u64 v[52:53], v[2:3], 0, v[52:53]
	v_lshl_add_u64 v[54:55], v[2:3], 0, v[54:55]
	v_lshl_add_u64 v[56:57], v[2:3], 0, v[56:57]
	v_lshl_add_u64 v[58:59], v[2:3], 0, v[58:59]
	v_lshl_add_u64 v[2:3], v[2:3], 0, v[60:61]
	s_waitcnt vmcnt(0) lgkmcnt(0)
	ds_write2_b32 v30, v4, v5 offset1:1
	ds_write2_b32 v30, v6, v7 offset0:2 offset1:3
	ds_write2_b32 v29, v8, v9 offset1:1
	ds_write2_b32 v31, v10, v11 offset1:1
	ds_write2_b32 v62, v12, v13 offset1:1
	ds_write2_b32 v63, v14, v15 offset1:1
	ds_write2_b32 v64, v20, v21 offset1:1
	ds_write2_b32 v65, v22, v23 offset1:1
	s_waitcnt lgkmcnt(0)
	s_barrier
	ds_read2_b32 v[4:5], v26 offset1:4
	ds_read2_b32 v[6:7], v26 offset0:8 offset1:12
	ds_read2_b32 v[8:9], v26 offset0:16 offset1:20
	ds_read2_b32 v[10:11], v26 offset0:24 offset1:28
	ds_read2_b32 v[12:13], v26 offset0:32 offset1:36
	ds_read2_b32 v[14:15], v26 offset0:40 offset1:44
	ds_read2_b32 v[20:21], v26 offset0:48 offset1:52
	ds_read2_b32 v[22:23], v26 offset0:56 offset1:60
	s_waitcnt lgkmcnt(7)
	v_cvt_pk_bf16_f32 v4, v4, s0
	v_cvt_pk_bf16_f32 v5, v5, s0
	s_waitcnt lgkmcnt(6)
	v_cvt_pk_bf16_f32 v6, v6, s0
	s_waitcnt lgkmcnt(1)
	v_cvt_pk_bf16_f32 v18, v20, s0
	v_cvt_pk_bf16_f32 v20, v21, s0
	s_waitcnt lgkmcnt(0)
	v_cvt_pk_bf16_f32 v21, v22, s0
	v_cvt_pk_bf16_f32 v22, v23, s0
	v_cvt_pk_bf16_f32 v7, v7, s0
	v_cvt_pk_bf16_f32 v8, v8, s0
	v_cvt_pk_bf16_f32 v9, v9, s0
	v_cvt_pk_bf16_f32 v10, v10, s0
	v_cvt_pk_bf16_f32 v11, v11, s0
	v_cvt_pk_bf16_f32 v12, v12, s0
	v_cvt_pk_bf16_f32 v13, v13, s0
	v_cvt_pk_bf16_f32 v14, v14, s0
	v_cvt_pk_bf16_f32 v15, v15, s0
	global_store_short v[16:17], v4, off
	global_store_short v[32:33], v5, off
	global_store_short v[34:35], v6, off
	global_store_short v[36:37], v7, off
	global_store_short v[38:39], v8, off
	global_store_short v[40:41], v9, off
	global_store_short v[42:43], v10, off
	global_store_short v[44:45], v11, off
	global_store_short v[46:47], v12, off
	global_store_short v[48:49], v13, off
	global_store_short v[50:51], v14, off
	global_store_short v[52:53], v15, off
	global_store_short v[54:55], v18, off
	global_store_short v[56:57], v20, off
	global_store_short v[58:59], v21, off
	global_store_short v[2:3], v22, off
	s_waitcnt lgkmcnt(0)
	s_barrier
	s_mov_b64 s[0:1], 0
